# final RMSNorm phase: gain vector loaded once before the row loop (was re-loaded per 16-byte piece behind a vmcnt(0) that also waited for the previous store); products in private registers
# baseline (speedup 1.0000x reference)
.LBB0_2462:
	v_readlane_b32 s18, v253, 50
	s_mov_b64 s[2:3], s[0:1]
	s_mov_b64 s[6:7], s[0:1]
	s_mov_b64 s[8:9], s[0:1]
	s_cmpk_gt_i32 s18, 0x210f
	v_readlane_b32 s19, v253, 51
	s_cbranch_scc1 .LBB0_2481
	s_load_dwordx2 s[4:5], s[2:3], 0xa8
	s_load_dwordx2 s[10:11], s[6:7], 0xb0
	s_load_dwordx2 s[12:13], s[8:9], 0xb0
	s_load_dwordx2 s[14:15], s[0:1], 0xa0
	v_and_b32_e32 v8, 63, v219
	v_mov_b32_e32 v3, 0
	v_lshlrev_b32_e32 v2, 3, v8
	v_lshlrev_b32_e32 v0, 2, v8
	v_mov_b32_e32 v1, v3
	s_waitcnt lgkmcnt(0)
	v_lshl_add_u64 v[4:5], s[10:11], 0, v[2:3]
	s_mov_b64 s[2:3], 0x11800000
	v_lshl_add_u64 v[4:5], v[4:5], 0, s[2:3]
	v_lshl_add_u64 v[6:7], s[12:13], 0, v[0:1]
	s_mov_b64 s[2:3], 0x32c40000
	v_lshlrev_b32_e32 v2, 4, v8
	v_cmp_gt_u32_e64 s[0:1], 32, v8
	v_lshl_add_u64 v[6:7], v[6:7], 0, s[2:3]
	v_lshl_add_u64 v[8:9], s[14:15], 0, v[2:3]
	s_mov_b64 s[2:3], 0x1000
	v_lshl_add_u64 v[10:11], v[8:9], 0, s[2:3]
	s_mov_b64 s[2:3], 0x1400
	v_lshl_add_u64 v[12:13], v[8:9], 0, s[2:3]
	s_mov_b64 s[2:3], 0x1800
	s_add_u32 s6, s4, 0x4000000
	v_lshl_add_u64 v[14:15], v[8:9], 0, s[2:3]
	s_mov_b64 s[2:3], 0x1c00
	s_addc_u32 s7, s5, 0
	v_lshl_add_u64 v[16:17], v[8:9], 0, s[2:3]
	s_lshl_b32 s12, s74, 4
	s_mov_b32 s9, 0
	v_mov_b32_e32 v1, 0x358637bd
	s_mov_b32 s13, 0xf800000
	v_mov_b32_e32 v50, 0x260
	s_movk_i32 s14, 0x1000
	global_load_dwordx4 v[64:67], v[8:9], off
	global_load_dwordx4 v[68:71], v[8:9], off offset:1024
	global_load_dwordx4 v[72:75], v[8:9], off offset:2048
	global_load_dwordx4 v[76:79], v[8:9], off offset:3072
	global_load_dwordx4 v[80:83], v[10:11], off
	global_load_dwordx4 v[84:87], v[12:13], off
	global_load_dwordx4 v[88:91], v[14:15], off
	global_load_dwordx4 v[92:95], v[16:17], off
	s_branch .LBB0_2465

.LBB0_2465:
	s_ashr_i32 s19, s18, 31
	s_waitcnt vmcnt(0)
	v_mov_b32_e32 v2, 0
	s_and_saveexec_b64 s[2:3], s[0:1]
	s_cbranch_execz .LBB0_2467
	s_lshl_b64 s[10:11], s[18:19], 7
	s_waitcnt vmcnt(0)
	v_lshl_add_u64 v[18:19], v[6:7], 0, s[10:11]
	global_load_dword v2, v[18:19], off

.LBB0_2472:
	s_waitcnt vmcnt(16)
	v_add_f32_dpp v58, v2, v2 quad_perm:[1,0,3,2] row_mask:0xf bank_mask:0xf bound_ctrl:1
	s_add_i32 s8, s18, s8
	s_waitcnt vmcnt(15)
	v_lshlrev_b32_e32 v56, 16, v48
	v_add_f32_dpp v58, v58, v58 quad_perm:[2,3,0,1] row_mask:0xf bank_mask:0xf bound_ctrl:1
	v_and_b32_e32 v57, 0xffff0000, v48
	v_lshlrev_b32_e32 v48, 16, v49
	v_add_f32_dpp v58, v58, v58 row_shr:4 row_mask:0xf bank_mask:0xf bound_ctrl:1
	v_and_b32_e32 v49, 0xffff0000, v49
	v_lshlrev_b32_e32 v2, 2, v0
	v_add_f32_dpp v58, v58, v58 row_shr:8 row_mask:0xf bank_mask:0xf bound_ctrl:1
	s_nop 0
	v_readlane_b32 s3, v58, 31
	v_readlane_b32 s2, v58, 15
	v_readlane_b32 s16, v58, 47
	v_readlane_b32 s17, v58, 63
	v_mov_b32_e32 v58, s3
	v_add_f32_e32 v58, s2, v58
	v_add_f32_e32 v58, s16, v58
	v_add_f32_e32 v58, s17, v58
	v_fmamk_f32 v58, v58, 0x3a000000, v1
	v_mul_f32_e32 v59, 0x4f800000, v58
	v_cmp_gt_f32_e32 vcc, s13, v58
	s_lshl_b64 s[16:17], s[8:9], 13
	s_add_u32 s10, s10, s16
	v_cndmask_b32_e32 v58, v58, v59, vcc
	v_sqrt_f32_e32 v59, v58
	s_addc_u32 s11, s11, s17
	s_mov_b32 s16, 0
	v_add_u32_e32 v60, -1, v59
	v_add_u32_e32 v61, 1, v59
	v_fma_f32 v62, -v60, v59, v58
	v_fma_f32 v63, -v61, v59, v58
	v_cmp_ge_f32_e64 s[2:3], 0, v62
	s_nop 1
	v_cndmask_b32_e64 v59, v59, v60, s[2:3]
	v_cmp_lt_f32_e64 s[2:3], 0, v63
	s_nop 1
	v_cndmask_b32_e64 v59, v59, v61, s[2:3]
	v_mul_f32_e32 v60, 0x37800000, v59
	v_cndmask_b32_e32 v59, v59, v60, vcc
	v_cmp_class_f32_e32 vcc, v58, v50
	s_nop 1
	v_cndmask_b32_e32 v58, v59, v58, vcc
	v_div_scale_f32 v59, s[2:3], v58, v58, 1.0
	v_rcp_f32_e32 v60, v59
	v_div_scale_f32 v61, vcc, 1.0, v58, 1.0
	v_fma_f32 v62, -v59, v60, 1.0
	v_fmac_f32_e32 v60, v62, v60
	v_mul_f32_e32 v62, v61, v60
	v_fma_f32 v63, -v59, v62, v61
	v_fmac_f32_e32 v62, v63, v60
	v_fma_f32 v59, -v59, v62, v61
	v_div_fmas_f32 v59, v59, v60, v62
	v_div_fixup_f32 v58, v59, v58, 1.0
	v_pk_mul_f32 v[56:57], v[58:59], v[56:57] op_sel_hi:[0,1]
	v_pk_mul_f32 v[48:49], v[58:59], v[48:49] op_sel_hi:[0,1]
	s_waitcnt vmcnt(0)
	v_pk_mul_f32 v[98:99], v[66:67], v[48:49]
	v_pk_mul_f32 v[96:97], v[64:65], v[56:57]
	global_store_dwordx4 v2, v[96:99], s[10:11]
	v_lshlrev_b32_e32 v48, 16, v46
	v_and_b32_e32 v49, 0xffff0000, v46
	v_lshlrev_b32_e32 v46, 16, v47
	v_and_b32_e32 v47, 0xffff0000, v47
	v_pk_mul_f32 v[56:57], v[58:59], v[46:47] op_sel_hi:[0,1]
	v_pk_mul_f32 v[46:47], v[58:59], v[48:49] op_sel_hi:[0,1]
	v_pk_mul_f32 v[100:101], v[68:69], v[46:47]
	v_pk_mul_f32 v[102:103], v[70:71], v[56:57]
	global_store_dwordx4 v2, v[100:103], s[10:11] offset:1024
	v_lshlrev_b32_e32 v52, 16, v44
	v_and_b32_e32 v53, 0xffff0000, v44
	v_lshlrev_b32_e32 v44, 16, v45
	v_and_b32_e32 v45, 0xffff0000, v45
	v_pk_mul_f32 v[54:55], v[58:59], v[44:45] op_sel_hi:[0,1]
	v_pk_mul_f32 v[44:45], v[58:59], v[52:53] op_sel_hi:[0,1]
	v_pk_mul_f32 v[104:105], v[72:73], v[44:45]
	v_pk_mul_f32 v[106:107], v[74:75], v[54:55]
	global_store_dwordx4 v2, v[104:107], s[10:11] offset:2048
	v_lshlrev_b32_e32 v48, 16, v42
	v_and_b32_e32 v49, 0xffff0000, v42
	v_lshlrev_b32_e32 v42, 16, v43
	v_and_b32_e32 v43, 0xffff0000, v43
	v_pk_mul_f32 v[52:53], v[58:59], v[42:43] op_sel_hi:[0,1]
	v_pk_mul_f32 v[42:43], v[58:59], v[48:49] op_sel_hi:[0,1]
	v_lshl_add_u64 v[48:49], s[10:11], 0, v[2:3]
	v_add_co_u32_e32 v48, vcc, s14, v48
	v_pk_mul_f32 v[108:109], v[76:77], v[42:43]
	v_pk_mul_f32 v[110:111], v[78:79], v[52:53]
	global_store_dwordx4 v2, v[108:111], s[10:11] offset:3072
	v_lshlrev_b32_e32 v46, 16, v40
	v_and_b32_e32 v47, 0xffff0000, v40
	v_lshlrev_b32_e32 v40, 16, v41
	v_and_b32_e32 v41, 0xffff0000, v41
	v_pk_mul_f32 v[52:53], v[58:59], v[40:41] op_sel_hi:[0,1]
	v_pk_mul_f32 v[40:41], v[58:59], v[46:47] op_sel_hi:[0,1]
	v_addc_co_u32_e32 v49, vcc, 0, v49, vcc
	v_pk_mul_f32 v[112:113], v[80:81], v[40:41]
	v_pk_mul_f32 v[114:115], v[82:83], v[52:53]
	global_store_dwordx4 v[48:49], v[112:115], off
	v_lshlrev_b32_e32 v44, 16, v38
	v_and_b32_e32 v45, 0xffff0000, v38
	v_lshlrev_b32_e32 v38, 16, v39
	v_and_b32_e32 v39, 0xffff0000, v39
	v_pk_mul_f32 v[46:47], v[58:59], v[38:39] op_sel_hi:[0,1]
	v_pk_mul_f32 v[38:39], v[58:59], v[44:45] op_sel_hi:[0,1]
	v_pk_mul_f32 v[116:117], v[84:85], v[38:39]
	v_pk_mul_f32 v[118:119], v[86:87], v[46:47]
	global_store_dwordx4 v[48:49], v[116:119], off offset:1024
	v_lshlrev_b32_e32 v42, 16, v36
	v_and_b32_e32 v43, 0xffff0000, v36
	v_lshlrev_b32_e32 v36, 16, v37
	v_and_b32_e32 v37, 0xffff0000, v37
	v_pk_mul_f32 v[44:45], v[58:59], v[36:37] op_sel_hi:[0,1]
	v_pk_mul_f32 v[36:37], v[58:59], v[42:43] op_sel_hi:[0,1]
	v_pk_mul_f32 v[120:121], v[88:89], v[36:37]
	v_pk_mul_f32 v[122:123], v[90:91], v[44:45]
	global_store_dwordx4 v[48:49], v[120:123], off offset:2048
	v_lshlrev_b32_e32 v40, 16, v34
	v_and_b32_e32 v41, 0xffff0000, v34
	v_lshlrev_b32_e32 v34, 16, v35
	v_and_b32_e32 v35, 0xffff0000, v35
	v_pk_mul_f32 v[42:43], v[58:59], v[34:35] op_sel_hi:[0,1]
	v_pk_mul_f32 v[34:35], v[58:59], v[40:41] op_sel_hi:[0,1]
	v_pk_mul_f32 v[124:125], v[92:93], v[34:35]
	v_pk_mul_f32 v[126:127], v[94:95], v[42:43]
	global_store_dwordx4 v[48:49], v[124:127], off offset:3072

.LBB0_2480:
	s_waitcnt vmcnt(8)
	v_add_f32_dpp v40, v51, v51 quad_perm:[1,0,3,2] row_mask:0xf bank_mask:0xf bound_ctrl:1
	s_add_i32 s8, s15, s8
	s_waitcnt vmcnt(7)
	v_lshlrev_b32_e32 v38, 16, v32
	v_add_f32_dpp v40, v40, v40 quad_perm:[2,3,0,1] row_mask:0xf bank_mask:0xf bound_ctrl:1
	v_and_b32_e32 v39, 0xffff0000, v32
	v_lshlrev_b32_e32 v32, 16, v33
	v_add_f32_dpp v40, v40, v40 row_shr:4 row_mask:0xf bank_mask:0xf bound_ctrl:1
	v_and_b32_e32 v33, 0xffff0000, v33
	v_lshlrev_b32_e32 v2, 2, v0
	v_add_f32_dpp v40, v40, v40 row_shr:8 row_mask:0xf bank_mask:0xf bound_ctrl:1
	s_nop 0
	v_readlane_b32 s3, v40, 31
	v_readlane_b32 s2, v40, 15
	v_readlane_b32 s15, v40, 47
	v_readlane_b32 s16, v40, 63
	v_mov_b32_e32 v40, s3
	v_add_f32_e32 v40, s2, v40
	v_add_f32_e32 v40, s15, v40
	v_add_f32_e32 v40, s16, v40
	v_fmamk_f32 v40, v40, 0x3a000000, v1
	v_mul_f32_e32 v41, 0x4f800000, v40
	v_cmp_gt_f32_e32 vcc, s13, v40
	s_lshl_b64 s[16:17], s[8:9], 13
	s_add_u32 s10, s10, s16
	v_cndmask_b32_e32 v40, v40, v41, vcc
	v_sqrt_f32_e32 v41, v40
	s_addc_u32 s11, s11, s17
	v_add_u32_e32 v42, -1, v41
	v_add_u32_e32 v43, 1, v41
	v_fma_f32 v44, -v42, v41, v40
	v_fma_f32 v45, -v43, v41, v40
	v_cmp_ge_f32_e64 s[2:3], 0, v44
	s_nop 1
	v_cndmask_b32_e64 v41, v41, v42, s[2:3]
	v_cmp_lt_f32_e64 s[2:3], 0, v45
	s_nop 1
	v_cndmask_b32_e64 v41, v41, v43, s[2:3]
	v_mul_f32_e32 v42, 0x37800000, v41
	v_cndmask_b32_e32 v41, v41, v42, vcc
	v_cmp_class_f32_e32 vcc, v40, v50
	s_nop 1
	v_cndmask_b32_e32 v40, v41, v40, vcc
	v_div_scale_f32 v41, s[2:3], v40, v40, 1.0
	v_rcp_f32_e32 v42, v41
	v_div_scale_f32 v43, vcc, 1.0, v40, 1.0
	v_fma_f32 v44, -v41, v42, 1.0
	v_fmac_f32_e32 v42, v44, v42
	v_mul_f32_e32 v44, v43, v42
	v_fma_f32 v45, -v41, v44, v43
	v_fmac_f32_e32 v44, v45, v42
	v_fma_f32 v41, -v41, v44, v43
	v_div_fmas_f32 v41, v41, v42, v44
	v_div_fixup_f32 v40, v41, v40, 1.0
	v_pk_mul_f32 v[38:39], v[40:41], v[38:39] op_sel_hi:[0,1]
	v_pk_mul_f32 v[32:33], v[40:41], v[32:33] op_sel_hi:[0,1]
	s_waitcnt vmcnt(0)
	v_pk_mul_f32 v[130:131], v[66:67], v[32:33]
	v_pk_mul_f32 v[128:129], v[64:65], v[38:39]
	global_store_dwordx4 v2, v[128:131], s[10:11]
	s_nop 0
	v_lshlrev_b32_e32 v36, 16, v30
	v_and_b32_e32 v37, 0xffff0000, v30
	v_lshlrev_b32_e32 v30, 16, v31
	v_and_b32_e32 v31, 0xffff0000, v31
	v_pk_mul_f32 v[38:39], v[40:41], v[30:31] op_sel_hi:[0,1]
	v_pk_mul_f32 v[30:31], v[40:41], v[36:37] op_sel_hi:[0,1]
	v_pk_mul_f32 v[132:133], v[68:69], v[30:31]
	v_pk_mul_f32 v[134:135], v[70:71], v[38:39]
	global_store_dwordx4 v2, v[132:135], s[10:11] offset:1024
	v_lshlrev_b32_e32 v34, 16, v28
	v_and_b32_e32 v35, 0xffff0000, v28
	v_lshlrev_b32_e32 v28, 16, v29
	v_and_b32_e32 v29, 0xffff0000, v29
	v_pk_mul_f32 v[36:37], v[40:41], v[28:29] op_sel_hi:[0,1]
	v_pk_mul_f32 v[28:29], v[40:41], v[34:35] op_sel_hi:[0,1]
	v_pk_mul_f32 v[136:137], v[72:73], v[28:29]
	v_pk_mul_f32 v[138:139], v[74:75], v[36:37]
	global_store_dwordx4 v2, v[136:139], s[10:11] offset:2048
	v_lshlrev_b32_e32 v32, 16, v26
	v_and_b32_e32 v33, 0xffff0000, v26
	v_lshlrev_b32_e32 v26, 16, v27
	v_and_b32_e32 v27, 0xffff0000, v27
	v_pk_mul_f32 v[34:35], v[40:41], v[26:27] op_sel_hi:[0,1]
	v_pk_mul_f32 v[26:27], v[40:41], v[32:33] op_sel_hi:[0,1]
	v_lshl_add_u64 v[32:33], s[10:11], 0, v[2:3]
	v_add_co_u32_e32 v32, vcc, s14, v32
	v_pk_mul_f32 v[140:141], v[76:77], v[26:27]
	v_pk_mul_f32 v[142:143], v[78:79], v[34:35]
	global_store_dwordx4 v2, v[140:143], s[10:11] offset:3072
	v_lshlrev_b32_e32 v30, 16, v24
	v_and_b32_e32 v31, 0xffff0000, v24
	v_lshlrev_b32_e32 v24, 16, v25
	v_and_b32_e32 v25, 0xffff0000, v25
	v_pk_mul_f32 v[34:35], v[40:41], v[24:25] op_sel_hi:[0,1]
	v_pk_mul_f32 v[24:25], v[40:41], v[30:31] op_sel_hi:[0,1]
	v_addc_co_u32_e32 v33, vcc, 0, v33, vcc
	v_pk_mul_f32 v[144:145], v[80:81], v[24:25]
	v_pk_mul_f32 v[146:147], v[82:83], v[34:35]
	global_store_dwordx4 v[32:33], v[144:147], off
	v_lshlrev_b32_e32 v28, 16, v22
	v_and_b32_e32 v29, 0xffff0000, v22
	v_lshlrev_b32_e32 v22, 16, v23
	v_and_b32_e32 v23, 0xffff0000, v23
	v_pk_mul_f32 v[30:31], v[40:41], v[22:23] op_sel_hi:[0,1]
	v_pk_mul_f32 v[22:23], v[40:41], v[28:29] op_sel_hi:[0,1]
	v_pk_mul_f32 v[148:149], v[84:85], v[22:23]
	v_pk_mul_f32 v[150:151], v[86:87], v[30:31]
	global_store_dwordx4 v[32:33], v[148:151], off offset:1024
	v_lshlrev_b32_e32 v26, 16, v20
	v_and_b32_e32 v27, 0xffff0000, v20
	v_lshlrev_b32_e32 v20, 16, v21
	v_and_b32_e32 v21, 0xffff0000, v21
	v_pk_mul_f32 v[28:29], v[40:41], v[20:21] op_sel_hi:[0,1]
	v_pk_mul_f32 v[20:21], v[40:41], v[26:27] op_sel_hi:[0,1]
	v_pk_mul_f32 v[152:153], v[88:89], v[20:21]
	v_pk_mul_f32 v[154:155], v[90:91], v[28:29]
	global_store_dwordx4 v[32:33], v[152:155], off offset:2048
	v_lshlrev_b32_e32 v24, 16, v18
	v_and_b32_e32 v25, 0xffff0000, v18
	v_lshlrev_b32_e32 v18, 16, v19
	v_and_b32_e32 v19, 0xffff0000, v19
	v_pk_mul_f32 v[26:27], v[40:41], v[18:19] op_sel_hi:[0,1]
	v_pk_mul_f32 v[18:19], v[40:41], v[24:25] op_sel_hi:[0,1]
	v_pk_mul_f32 v[156:157], v[92:93], v[18:19]
	v_pk_mul_f32 v[158:159], v[94:95], v[26:27]
	global_store_dwordx4 v[32:33], v[156:159], off offset:3072
	s_branch .LBB0_2464
